# v81 with the younger half-workgroup one priority level above the older half in every phase (A 0/1/2, B 1/2/3)
# baseline (speedup 1.0000x reference)
; DI void expsum(f32x16& p, float& l_reg, bf16x8& pa0, bf16x8& pa1) {
; #pragma unroll
;     for (int r = 0; r < 16; ++r) p[r] = __builtin_amdgcn_exp2f(p[r]);
;     float ps = 0.f;
; #pragma unroll
;     for (int r = 0; r < 16; ++r) ps += p[r];
;     l_reg += ps; asm volatile("" : "+v"(l_reg));
;     ...
;     ATT_PK4(p, 0, pa0); ATT_PK4(p, 8, pa1);
;     ...
; }
; DI int v_rd_base(int lane) { return ((lane & 3) << 3) | (((lane >> 2) & 3) << 6) | (((lane >> 4) & 1) << 5) | (((lane >> 5) & 1) << 8); }
; template <int OFF> DI s16x4 tr_read(int vb) { s16x4 r; asm volatile("ds_read_b64_tr_b16 %0, %1 offset:%2" : "=&v"(r) : "v"(vb), "i"(OFF) : "memory"); return r; }
; template <int H> DI void v_reads(s16x4* vf, int vb) {
;     vf[0] = tr_read<v_rd_off(0, 2 * H, 0)>(vb); vf[1] = tr_read<v_rd_off(0, 2 * H, 1)>(vb); vf[2] = tr_read<v_rd_off(0, 2 * H + 1, 0)>(vb); vf[3] = tr_read<v_rd_off(0, 2 * H + 1, 1)>(vb);
;     vf[4] = tr_read<v_rd_off(1, 2 * H, 0)>(vb); vf[5] = tr_read<v_rd_off(1, 2 * H, 1)>(vb); vf[6] = tr_read<v_rd_off(1, 2 * H + 1, 0)>(vb); vf[7] = tr_read<v_rd_off(1, 2 * H + 1, 1)>(vb);
;     vf[8] = tr_read<v_rd_off(2, 2 * H, 0)>(vb); vf[9] = tr_read<v_rd_off(2, 2 * H, 1)>(vb); vf[10] = tr_read<v_rd_off(2, 2 * H + 1, 0)>(vb); vf[11] = tr_read<v_rd_off(2, 2 * H + 1, 1)>(vb);
;     vf[12] = tr_read<v_rd_off(3, 2 * H, 0)>(vb); vf[13] = tr_read<v_rd_off(3, 2 * H, 1)>(vb); vf[14] = tr_read<v_rd_off(3, 2 * H + 1, 0)>(vb); vf[15] = tr_read<v_rd_off(3, 2 * H + 1, 1)>(vb);
; }
; DI void pv_mma(f32x16* o, const s16x4* vf, bf16x8 pa0, bf16x8 pa1) {
;     ...
; #pragma unroll
;     for (int d0 = 0; d0 < 4; ++d0) {
;         o[d0] = __builtin_amdgcn_mfma_f32_32x32x16_bf16(pa0, ATT_PK(vf[4 * d0], vf[4 * d0 + 1]), o[d0], 0, 0, 0);
;         o[d0] = __builtin_amdgcn_mfma_f32_32x32x16_bf16(pa1, ATT_PK(vf[4 * d0 + 2], vf[4 * d0 + 3]), o[d0], 0, 0, 0); }
;     ...
; }
.Lhw_d0_b_n1920:
	s_and_b32 s1, s22, 0x6000
	s_add_i32 m0, s59, s1
	s_lshl_b32 s1, s96, 14
	s_setprio 1
	s_add_i32 s1, s95, s1
	global_load_lds_dwordx4 v100, s[34:35]
	s_add_i32 s2, s1, 0x400
	s_mov_b32 m0, s1
	s_sub_i32 s74, s0, s98
	global_load_lds_dwordx4 v102, s[34:35]
	s_mov_b32 m0, s2
	s_cmp_le_u32 s74, s101
	global_load_lds_dwordx4 v104, s[34:35]
	s_mov_b32 s1, s23
	s_cbranch_scc1 .Lhw_d0_b_dtd0resc
.Lhw_d0_b_n1922:
	ds_read_b128 v[122:125], v196 offset:4096
	ds_read_b128 v[132:135], v197 offset:4096
	s_lshl_b32 s2, s1, 14
	ds_read_b128 v[136:139], v198 offset:4096
	ds_read_b128 v[140:143], v199 offset:4096
	ds_read_b64_tr_b16 v[144:145], v121 offset:0
	ds_read_b64_tr_b16 v[146:147], v121 offset:0x800
	ds_read_b64_tr_b16 v[148:149], v121 offset:0x1000
	ds_read_b64_tr_b16 v[150:151], v121 offset:0x1800
	ds_read_b64_tr_b16 v[152:153], v121 offset:0x200
	ds_read_b64_tr_b16 v[154:155], v121 offset:0xa00
	ds_read_b64_tr_b16 v[156:157], v121 offset:0x1200
	ds_read_b64_tr_b16 v[158:159], v121 offset:0x1a00
	ds_read_b64_tr_b16 v[162:163], v121 offset:0x400
	ds_read_b64_tr_b16 v[164:165], v121 offset:0xc00
	ds_read_b64_tr_b16 v[166:167], v121 offset:0x1400
	ds_read_b64_tr_b16 v[168:169], v121 offset:0x1c00
	ds_read_b64_tr_b16 v[170:171], v121 offset:0x600
	ds_read_b64_tr_b16 v[172:173], v121 offset:0xe00
	ds_read_b64_tr_b16 v[174:175], v121 offset:0x1600
	ds_read_b64_tr_b16 v[176:177], v121 offset:0x1e00
	s_setprio 2
	v_exp_f32_e32 v64, v64
	v_exp_f32_e32 v65, v65
	v_exp_f32_e32 v66, v66
	v_exp_f32_e32 v67, v67
	v_exp_f32_e32 v68, v68
	v_exp_f32_e32 v69, v69
	v_add_f32_e32 v126, v65, v64
	v_exp_f32_e32 v70, v70
	v_add_f32_e32 v126, v66, v126
	v_exp_f32_e32 v71, v71
	v_add_f32_e32 v126, v67, v126
	v_exp_f32_e32 v72, v72
	v_add_f32_e32 v126, v68, v126
	v_exp_f32_e32 v73, v73
	v_add_f32_e32 v126, v69, v126
	v_exp_f32_e32 v74, v74
	v_add_f32_e32 v126, v70, v126
	v_exp_f32_e32 v75, v75
	v_add_f32_e32 v126, v71, v126
	v_exp_f32_e32 v76, v76
	v_add_f32_e32 v126, v72, v126
	v_exp_f32_e32 v77, v77
	v_add_f32_e32 v126, v73, v126
	v_exp_f32_e32 v78, v78
	v_add_f32_e32 v126, v74, v126
	v_exp_f32_e32 v79, v79
	v_add_f32_e32 v126, v75, v126
	v_add_f32_e32 v126, v76, v126
	v_add_f32_e32 v126, v77, v126
	v_add_f32_e32 v126, v78, v126
	v_add_f32_e32 v126, v79, v126
	v_add_f32_e32 v120, v126, v120
	v_cvt_pk_bf16_f32 v64, v64, v65
	v_cvt_pk_bf16_f32 v65, v66, v67
	v_cvt_pk_bf16_f32 v66, v68, v69
	v_cvt_pk_bf16_f32 v67, v70, v71
	v_cvt_pk_bf16_f32 v68, v72, v73
	v_cvt_pk_bf16_f32 v69, v74, v75
	v_cvt_pk_bf16_f32 v70, v76, v77
	v_cvt_pk_bf16_f32 v71, v78, v79
	s_waitcnt lgkmcnt(0)
	s_setprio 3
	v_mfma_f32_32x32x16_bf16 v[0:15], v[64:67], v[144:147], v[0:15]
	s_add_i32 s74, s22, 0xffffc000
	s_and_b32 s74, s74, 0x6000
	s_sub_i32 s3, s0, s98
	s_cmp_lt_u32 s3, s100
	v_mfma_f32_32x32x16_bf16 v[48:63], v[64:67], v[152:155], v[48:63]
	v_mfma_f32_32x32x16_bf16 v[32:47], v[64:67], v[162:165], v[32:47]
	v_mfma_f32_32x32x16_bf16 v[16:31], v[64:67], v[170:173], v[16:31]
	v_mfma_f32_32x32x16_bf16 v[0:15], v[68:71], v[148:151], v[0:15]
	v_mfma_f32_32x32x16_bf16 v[48:63], v[68:71], v[156:159], v[48:63]
	v_mfma_f32_32x32x16_bf16 v[32:47], v[68:71], v[166:169], v[32:47]
	v_mfma_f32_32x32x16_bf16 v[16:31], v[68:71], v[174:177], v[16:31]
	v_add_u32_e32 v196, s74, v107
	v_mfma_f32_32x32x16_bf16 v[64:79], v[122:125], v[92:95], 0
	v_add_u32_e32 v197, s74, v108
	v_mfma_f32_32x32x16_bf16 v[64:79], v[132:135], v[88:91], v[64:79]
	v_add_u32_e32 v198, s74, v109
	v_mfma_f32_32x32x16_bf16 v[64:79], v[136:139], v[84:87], v[64:79]
	v_add_u32_e32 v199, s74, v110
	v_mfma_f32_32x32x16_bf16 v[64:79], v[140:143], v[80:83], v[64:79]
	s_setprio 1
	s_cbranch_scc1 .Lhw_d0_b_dtd0bias1

; DI void expsum(f32x16& p, float& l_reg, bf16x8& pa0, bf16x8& pa1) {
; #pragma unroll
;     for (int r = 0; r < 16; ++r) p[r] = __builtin_amdgcn_exp2f(p[r]);
;     float ps = 0.f;
; #pragma unroll
;     for (int r = 0; r < 16; ++r) ps += p[r];
;     l_reg += ps; asm volatile("" : "+v"(l_reg));
;     ...
;     ATT_PK4(p, 0, pa0); ATT_PK4(p, 8, pa1);
;     ...
; }
; DI int v_rd_base(int lane) { return ((lane & 3) << 3) | (((lane >> 2) & 3) << 6) | (((lane >> 4) & 1) << 5) | (((lane >> 5) & 1) << 8); }
; template <int OFF> DI s16x4 tr_read(int vb) { s16x4 r; asm volatile("ds_read_b64_tr_b16 %0, %1 offset:%2" : "=&v"(r) : "v"(vb), "i"(OFF) : "memory"); return r; }
; template <int H> DI void v_reads(s16x4* vf, int vb) {
;     vf[0] = tr_read<v_rd_off(0, 2 * H, 0)>(vb); vf[1] = tr_read<v_rd_off(0, 2 * H, 1)>(vb); vf[2] = tr_read<v_rd_off(0, 2 * H + 1, 0)>(vb); vf[3] = tr_read<v_rd_off(0, 2 * H + 1, 1)>(vb);
;     vf[4] = tr_read<v_rd_off(1, 2 * H, 0)>(vb); vf[5] = tr_read<v_rd_off(1, 2 * H, 1)>(vb); vf[6] = tr_read<v_rd_off(1, 2 * H + 1, 0)>(vb); vf[7] = tr_read<v_rd_off(1, 2 * H + 1, 1)>(vb);
;     vf[8] = tr_read<v_rd_off(2, 2 * H, 0)>(vb); vf[9] = tr_read<v_rd_off(2, 2 * H, 1)>(vb); vf[10] = tr_read<v_rd_off(2, 2 * H + 1, 0)>(vb); vf[11] = tr_read<v_rd_off(2, 2 * H + 1, 1)>(vb);
;     vf[12] = tr_read<v_rd_off(3, 2 * H, 0)>(vb); vf[13] = tr_read<v_rd_off(3, 2 * H, 1)>(vb); vf[14] = tr_read<v_rd_off(3, 2 * H + 1, 0)>(vb); vf[15] = tr_read<v_rd_off(3, 2 * H + 1, 1)>(vb);
; }
; DI void pv_mma(f32x16* o, const s16x4* vf, bf16x8 pa0, bf16x8 pa1) {
;     ...
; #pragma unroll
;     for (int d0 = 0; d0 < 4; ++d0) {
;         o[d0] = __builtin_amdgcn_mfma_f32_32x32x16_bf16(pa0, ATT_PK(vf[4 * d0], vf[4 * d0 + 1]), o[d0], 0, 0, 0);
;         o[d0] = __builtin_amdgcn_mfma_f32_32x32x16_bf16(pa1, ATT_PK(vf[4 * d0 + 2], vf[4 * d0 + 3]), o[d0], 0, 0, 0); }
;     ...
; }
.Lhw_d1_b_n1951:
	s_and_b32 s2, s22, 0x6000
	s_add_i32 m0, s94, s2
	s_lshl_b32 s2, s1, 14
	s_setprio 1
	s_add_i32 s2, s48, s2
	global_load_lds_dwordx4 v100, s[34:35]
	s_add_i32 s3, s2, 0x400
	s_mov_b32 m0, s2
	s_sub_i32 s74, s0, s98
	global_load_lds_dwordx4 v102, s[34:35]
	s_mov_b32 m0, s3
	s_cmp_le_u32 s74, s101
	global_load_lds_dwordx4 v104, s[34:35]
	s_mov_b32 s23, s62
	s_cbranch_scc1 .Lhw_d1_b_dtd1resc
.Lhw_d1_b_n1953:
	ds_read_b128 v[122:125], v196 offset:4096
	ds_read_b128 v[132:135], v197 offset:4096
	s_lshl_b32 s2, s23, 14
	ds_read_b128 v[136:139], v198 offset:4096
	ds_read_b128 v[140:143], v199 offset:4096
	ds_read_b64_tr_b16 v[144:145], v121 offset:0
	ds_read_b64_tr_b16 v[146:147], v121 offset:0x800
	ds_read_b64_tr_b16 v[148:149], v121 offset:0x1000
	ds_read_b64_tr_b16 v[150:151], v121 offset:0x1800
	ds_read_b64_tr_b16 v[152:153], v121 offset:0x200
	ds_read_b64_tr_b16 v[154:155], v121 offset:0xa00
	ds_read_b64_tr_b16 v[156:157], v121 offset:0x1200
	ds_read_b64_tr_b16 v[158:159], v121 offset:0x1a00
	ds_read_b64_tr_b16 v[162:163], v121 offset:0x400
	ds_read_b64_tr_b16 v[164:165], v121 offset:0xc00
	ds_read_b64_tr_b16 v[166:167], v121 offset:0x1400
	ds_read_b64_tr_b16 v[168:169], v121 offset:0x1c00
	ds_read_b64_tr_b16 v[170:171], v121 offset:0x600
	ds_read_b64_tr_b16 v[172:173], v121 offset:0xe00
	ds_read_b64_tr_b16 v[174:175], v121 offset:0x1600
	ds_read_b64_tr_b16 v[176:177], v121 offset:0x1e00
	s_setprio 2
	v_exp_f32_e32 v64, v64
	v_exp_f32_e32 v65, v65
	v_exp_f32_e32 v66, v66
	v_exp_f32_e32 v67, v67
	v_exp_f32_e32 v68, v68
	v_exp_f32_e32 v69, v69
	v_add_f32_e32 v126, v65, v64
	v_exp_f32_e32 v70, v70
	v_add_f32_e32 v126, v66, v126
	v_exp_f32_e32 v71, v71
	v_add_f32_e32 v126, v67, v126
	v_exp_f32_e32 v72, v72
	v_add_f32_e32 v126, v68, v126
	v_exp_f32_e32 v73, v73
	v_add_f32_e32 v126, v69, v126
	v_exp_f32_e32 v74, v74
	v_add_f32_e32 v126, v70, v126
	v_exp_f32_e32 v75, v75
	v_add_f32_e32 v126, v71, v126
	v_exp_f32_e32 v76, v76
	v_add_f32_e32 v126, v72, v126
	v_exp_f32_e32 v77, v77
	v_add_f32_e32 v126, v73, v126
	v_exp_f32_e32 v78, v78
	v_add_f32_e32 v126, v74, v126
	v_exp_f32_e32 v79, v79
	v_add_f32_e32 v126, v75, v126
	v_add_f32_e32 v126, v76, v126
	v_add_f32_e32 v126, v77, v126
	v_add_f32_e32 v126, v78, v126
	v_add_f32_e32 v126, v79, v126
	v_add_f32_e32 v120, v126, v120
	v_cvt_pk_bf16_f32 v64, v64, v65
	v_cvt_pk_bf16_f32 v65, v66, v67
	v_cvt_pk_bf16_f32 v66, v68, v69
	v_cvt_pk_bf16_f32 v67, v70, v71
	v_cvt_pk_bf16_f32 v68, v72, v73
	v_cvt_pk_bf16_f32 v69, v74, v75
	v_cvt_pk_bf16_f32 v70, v76, v77
	v_cvt_pk_bf16_f32 v71, v78, v79
	s_waitcnt lgkmcnt(0)
	s_setprio 3
	v_mfma_f32_32x32x16_bf16 v[0:15], v[64:67], v[144:147], v[0:15]
	s_add_i32 s74, s22, 0xffffc000
	s_and_b32 s74, s74, 0x6000
	s_sub_i32 s3, s0, s98
	s_cmp_lt_u32 s3, s100
	v_mfma_f32_32x32x16_bf16 v[48:63], v[64:67], v[152:155], v[48:63]
	v_mfma_f32_32x32x16_bf16 v[16:31], v[64:67], v[162:165], v[16:31]
	v_mfma_f32_32x32x16_bf16 v[32:47], v[64:67], v[170:173], v[32:47]
	v_mfma_f32_32x32x16_bf16 v[0:15], v[68:71], v[148:151], v[0:15]
	v_mfma_f32_32x32x16_bf16 v[48:63], v[68:71], v[156:159], v[48:63]
	v_mfma_f32_32x32x16_bf16 v[16:31], v[68:71], v[166:169], v[16:31]
	v_mfma_f32_32x32x16_bf16 v[32:47], v[68:71], v[174:177], v[32:47]
	v_add_u32_e32 v196, s74, v107
	v_mfma_f32_32x32x16_bf16 v[64:79], v[122:125], v[92:95], 0
	v_add_u32_e32 v197, s74, v108
	v_mfma_f32_32x32x16_bf16 v[64:79], v[132:135], v[88:91], v[64:79]
	v_add_u32_e32 v198, s74, v109
	v_mfma_f32_32x32x16_bf16 v[64:79], v[136:139], v[84:87], v[64:79]
	v_add_u32_e32 v199, s74, v110
	v_mfma_f32_32x32x16_bf16 v[64:79], v[140:143], v[80:83], v[64:79]
	s_setprio 1
	s_cbranch_scc1 .Lhw_d1_b_dtd1bias1

; #define SBAR() __builtin_amdgcn_sched_barrier(0)
; #define ATT_DMA_K(t) do { const bf16_t* kg_ = Kh + (size_t)(t) * 64 * LDK; LAS unsigned char* sb_ = lds + ((t) & 3) * KBUF; \
;     _Pragma("unroll") for (int i_ = 0; i_ < NKP; ++i_) __builtin_amdgcn_global_load_lds((const unsigned*)(kg_ + kgo[i_]), (LAS unsigned*)(sb_ + (wid + 8 * i_) * 1024), 16, 0, 0); } while (0)
; #define ATT_DMA_V(t, vs) do { const bf16_t* vg_ = Vh + (size_t)(t) * 64 * LDV; LAS unsigned char* sb_ = lds + V_OFF + (vs) * SHM_V; \
;     _Pragma("unroll") for (int i_ = 0; i_ < 2; ++i_) __builtin_amdgcn_global_load_lds((const unsigned*)(vg_ + vgo[i_]), (LAS unsigned*)(sb_ + (2 * wid + i_) * 1024), 16, 0, 0); } while (0)
; #define ATT_SEG(t) do { if constexpr (MODE != 0) { if (((t) == tL && tL > 0) || (t) == tR) { const float f_ = (t) == tR ? fR : fL; l_reg *= f_; \
;     _Pragma("unroll") for (int d = 0; d < 4; ++d) _Pragma("unroll") for (int r = 0; r < 16; ++r) o[d][r] *= f_; } } } while (0)
; #define ATT_BIAS(P, t, half) do { if constexpr (MODE != 0) { if ((t) >= tL && (t) < tR) { const LAS float* bp_ = bt + ((t) * 64 + (half) * 32 - qpos + 224 + 4 * hi);     \
;     _Pragma("unroll") for (int r = 0; r < 16; ++r) P[r] += bp_[(r & 3) + 8 * (r >> 2)]; } } } while (0)
; #define ATT_TOP(N) do { asm volatile("s_waitcnt vmcnt(%0)" :: "n"(N) : "memory"); __builtin_amdgcn_s_barrier(); asm volatile("" ::: "memory"); } while (0)
; template <int DQK, int MODE, int LDQ, int LDK, int LDV> ...
;     ...
;     f32x16 pA, pB; bf16x8 pa0, pa1;
;     int v0 = 0, v1 = 1, v2 = 2;
;     ATT_TOP(NKP + 2);
;     { bf16x8 kf[NDA]; k_reads<DQK, 0, NDA>(kf, lds, 0, r32, hi); ATT_LGKM0(); qk_mma<0, NDA>(pA, kf, qr);
;       if constexpr (ND0 > NDA) { bf16x8 kg[ND0 - NDA]; k_reads<DQK, NDA, ND0>(kg, lds, 0, r32, hi); ATT_LGKM0(); qk_mma<NDA, ND0>(pA, kg, qr); }
;       ATT_BIAS(pA, 0, 0); }
;     if (wid >= 4) __builtin_amdgcn_s_setprio(1);
;     for (int j = 0; j < NT; ++j) {
;         if (j + 2 < NT) ATT_TOP(NKP + 2); else ATT_TOP(0);
;         if (j + 3 < NT) ATT_DMA_K(j + 3);
;         if (j + 2 < NT) ATT_DMA_V(j + 2, v2);
;         ATT_SEG(j); SBAR();
;         ATT_STEP(pA, pB, 0, v0, true, 1, j);
;         ATT_STEP(pB, pA, 1, v0, (j + 1 < NT), 0, j + 1);
;         { const int t_ = v0; v0 = v1; v1 = v2; v2 = t_; }
;     }
.Lhw_mla_b_n1982:
	s_and_b32 s1, s43, 3
	s_mulk_i32 s1, 0x6000
	s_add_i32 s1, s49, s1
	s_setprio 1
	s_mov_b32 m0, s1
	s_mov_b32 s0, s5
	s_mov_b32 s5, s44
	s_mov_b32 s44, s4
	s_lshl_b32 s4, s4, 14
	global_load_lds_dwordx4 v136, s[34:35]
	s_add_i32 m0, s1, 0x2000
	s_add_i32 s4, s52, s4
	global_load_lds_dwordx4 v138, s[34:35]
	s_add_i32 m0, s1, 0x4000
	s_add_i32 s6, s4, 0x400
	global_load_lds_dwordx4 v140, s[34:35]
	s_mov_b32 m0, s4
	s_add_i32 s1, s43, -3
	global_load_lds_dwordx4 v144, s[34:35]
	s_mov_b32 m0, s6
	s_nop 0
	global_load_lds_dwordx4 v142, s[34:35]
	s_and_b32 s1, s1, 3
	s_mulk_i32 s1, 0x6000
	v_add_u32_e32 v246, s1, v158
	v_add_u32_e32 v250, v246, v151
	v_add_u32_e32 v251, v246, v149
	v_add_u32_e32 v252, v246, v148
	v_add_u32_e32 v253, v246, v147
	s_lshl_b32 s1, s0, 14
	ds_read_b128 v[190:193], v250 offset:12416
	ds_read_b128 v[194:197], v251 offset:12416
	ds_read_b128 v[174:177], v250 offset:12288
	ds_read_b128 v[178:181], v251 offset:12288
	ds_read_b128 v[182:185], v252 offset:12288
	ds_read_b128 v[186:189], v253 offset:12288
	v_add_u32_e32 v254, s1, v130
	ds_read_b64_tr_b16 v[198:199], v254 offset:0
	ds_read_b64_tr_b16 v[200:201], v254 offset:0x800
	ds_read_b64_tr_b16 v[202:203], v254 offset:0x1000
	ds_read_b64_tr_b16 v[204:205], v254 offset:0x1800
	ds_read_b64_tr_b16 v[206:207], v254 offset:0x200
	ds_read_b64_tr_b16 v[208:209], v254 offset:0xa00
	ds_read_b64_tr_b16 v[210:211], v254 offset:0x1200
	ds_read_b64_tr_b16 v[212:213], v254 offset:0x1a00
	ds_read_b64_tr_b16 v[214:215], v254 offset:0x400
	ds_read_b64_tr_b16 v[216:217], v254 offset:0xc00
	ds_read_b64_tr_b16 v[218:219], v254 offset:0x1400
	ds_read_b64_tr_b16 v[220:221], v254 offset:0x1c00
	ds_read_b64_tr_b16 v[222:223], v254 offset:0x600
	ds_read_b64_tr_b16 v[224:225], v254 offset:0xe00
	ds_read_b64_tr_b16 v[226:227], v254 offset:0x1600
	ds_read_b64_tr_b16 v[228:229], v254 offset:0x1e00
	s_setprio 2
	v_exp_f32_e32 v64, v64
	v_exp_f32_e32 v65, v65
	v_exp_f32_e32 v66, v66
	v_exp_f32_e32 v67, v67
	v_exp_f32_e32 v68, v68
	v_exp_f32_e32 v69, v69
	v_add_f32_e32 v230, v65, v64
	v_exp_f32_e32 v70, v70
	v_add_f32_e32 v230, v66, v230
	v_exp_f32_e32 v71, v71
	v_add_f32_e32 v230, v67, v230
	v_exp_f32_e32 v72, v72
	v_add_f32_e32 v230, v68, v230
	v_exp_f32_e32 v73, v73
	v_add_f32_e32 v230, v69, v230
	v_exp_f32_e32 v74, v74
	v_add_f32_e32 v230, v70, v230
	v_exp_f32_e32 v75, v75
	v_add_f32_e32 v230, v71, v230
	v_exp_f32_e32 v76, v76
	v_add_f32_e32 v230, v72, v230
	v_exp_f32_e32 v77, v77
	v_add_f32_e32 v230, v73, v230
	v_exp_f32_e32 v78, v78
	v_add_f32_e32 v230, v74, v230
	v_exp_f32_e32 v79, v79
	v_add_f32_e32 v230, v75, v230
	v_add_f32_e32 v230, v76, v230
	v_add_f32_e32 v230, v77, v230
	v_add_f32_e32 v230, v78, v230
	v_add_f32_e32 v230, v79, v230
	v_add_f32_e32 v173, v173, v230
	v_cvt_pk_bf16_f32 v64, v64, v65
	v_cvt_pk_bf16_f32 v65, v66, v67
	v_cvt_pk_bf16_f32 v66, v68, v69
	v_cvt_pk_bf16_f32 v67, v70, v71
	v_cvt_pk_bf16_f32 v68, v72, v73
	v_cvt_pk_bf16_f32 v69, v74, v75
	v_cvt_pk_bf16_f32 v70, v76, v77
	v_cvt_pk_bf16_f32 v71, v78, v79
	s_waitcnt lgkmcnt(0)
	ds_read_b128 v[230:233], v252 offset:12416
	ds_read_b128 v[234:237], v253 offset:12416
	ds_read_b128 v[238:241], v250 offset:12544
	ds_read_b128 v[242:245], v251 offset:12544
	ds_read_b128 v[246:249], v252 offset:12544
	ds_read_b128 v[250:253], v253 offset:12544
	s_setprio 3
	v_mfma_f32_32x32x16_bf16 v[48:63], v[64:67], v[198:201], v[48:63]
	v_mfma_f32_32x32x16_bf16 v[32:47], v[64:67], v[206:209], v[32:47]
	v_mfma_f32_32x32x16_bf16 v[16:31], v[64:67], v[214:217], v[16:31]
	v_mfma_f32_32x32x16_bf16 v[0:15], v[64:67], v[222:225], v[0:15]
	v_mfma_f32_32x32x16_bf16 v[48:63], v[68:71], v[202:205], v[48:63]
	v_mfma_f32_32x32x16_bf16 v[32:47], v[68:71], v[210:213], v[32:47]
	v_mfma_f32_32x32x16_bf16 v[16:31], v[68:71], v[218:221], v[16:31]
	v_mfma_f32_32x32x16_bf16 v[0:15], v[68:71], v[226:229], v[0:15]
	s_waitcnt lgkmcnt(0)
; #define SBAR() __builtin_amdgcn_sched_barrier(0)
; #define ATT_DMA_K(t) do { const bf16_t* kg_ = Kh + (size_t)(t) * 64 * LDK; LAS unsigned char* sb_ = lds + ((t) & 3) * KBUF; \
;     _Pragma("unroll") for (int i_ = 0; i_ < NKP; ++i_) __builtin_amdgcn_global_load_lds((const unsigned*)(kg_ + kgo[i_]), (LAS unsigned*)(sb_ + (wid + 8 * i_) * 1024), 16, 0, 0); } while (0)
; #define ATT_DMA_V(t, vs) do { const bf16_t* vg_ = Vh + (size_t)(t) * 64 * LDV; LAS unsigned char* sb_ = lds + V_OFF + (vs) * SHM_V; \
;     _Pragma("unroll") for (int i_ = 0; i_ < 2; ++i_) __builtin_amdgcn_global_load_lds((const unsigned*)(vg_ + vgo[i_]), (LAS unsigned*)(sb_ + (2 * wid + i_) * 1024), 16, 0, 0); } while (0)
; #define ATT_SEG(t) do { if constexpr (MODE != 0) { if (((t) == tL && tL > 0) || (t) == tR) { const float f_ = (t) == tR ? fR : fL; l_reg *= f_; \
;     _Pragma("unroll") for (int d = 0; d < 4; ++d) _Pragma("unroll") for (int r = 0; r < 16; ++r) o[d][r] *= f_; } } } while (0)
; #define ATT_BIAS(P, t, half) do { if constexpr (MODE != 0) { if ((t) >= tL && (t) < tR) { const LAS float* bp_ = bt + ((t) * 64 + (half) * 32 - qpos + 224 + 4 * hi);     \
;     _Pragma("unroll") for (int r = 0; r < 16; ++r) P[r] += bp_[(r & 3) + 8 * (r >> 2)]; } } } while (0)
; #define ATT_TOP(N) do { asm volatile("s_waitcnt vmcnt(%0)" :: "n"(N) : "memory"); __builtin_amdgcn_s_barrier(); asm volatile("" ::: "memory"); } while (0)
; template <int DQK, int MODE, int LDQ, int LDK, int LDV> ...
;     ...
;     f32x16 pA, pB; bf16x8 pa0, pa1;
;     int v0 = 0, v1 = 1, v2 = 2;
;     ATT_TOP(NKP + 2);
;     { bf16x8 kf[NDA]; k_reads<DQK, 0, NDA>(kf, lds, 0, r32, hi); ATT_LGKM0(); qk_mma<0, NDA>(pA, kf, qr);
;       if constexpr (ND0 > NDA) { bf16x8 kg[ND0 - NDA]; k_reads<DQK, NDA, ND0>(kg, lds, 0, r32, hi); ATT_LGKM0(); qk_mma<NDA, ND0>(pA, kg, qr); }
;       ATT_BIAS(pA, 0, 0); }
;     if (wid >= 4) __builtin_amdgcn_s_setprio(1);
;     for (int j = 0; j < NT; ++j) {
;         if (j + 2 < NT) ATT_TOP(NKP + 2); else ATT_TOP(0);
;         if (j + 3 < NT) ATT_DMA_K(j + 3);
;         if (j + 2 < NT) ATT_DMA_V(j + 2, v2);
;         ATT_SEG(j); SBAR();
;         ATT_STEP(pA, pB, 0, v0, true, 1, j);
;         ATT_STEP(pB, pA, 1, v0, (j + 1 < NT), 0, j + 1);
;         { const int t_ = v0; v0 = v1; v1 = v2; v2 = t_; }
;     }
	v_mfma_f32_32x32x16_bf16 v[64:79], v[174:177], v[80:83], 0
	v_mfma_f32_32x32x16_bf16 v[64:79], v[178:181], v[84:87], v[64:79]
	v_mfma_f32_32x32x16_bf16 v[64:79], v[182:185], v[88:91], v[64:79]
	v_mfma_f32_32x32x16_bf16 v[64:79], v[186:189], v[92:95], v[64:79]
	v_mfma_f32_32x32x16_bf16 v[64:79], v[190:193], v[96:99], v[64:79]
	v_mfma_f32_32x32x16_bf16 v[64:79], v[194:197], v[100:103], v[64:79]
	v_mfma_f32_32x32x16_bf16 v[64:79], v[230:233], v[104:107], v[64:79]
	v_mfma_f32_32x32x16_bf16 v[64:79], v[234:237], v[108:111], v[64:79]
	v_mfma_f32_32x32x16_bf16 v[64:79], v[238:241], v[112:115], v[64:79]
	v_mfma_f32_32x32x16_bf16 v[64:79], v[242:245], v[116:119], v[64:79]
	v_mfma_f32_32x32x16_bf16 v[64:79], v[246:249], v[120:123], v[64:79]
	v_mfma_f32_32x32x16_bf16 v[64:79], v[250:253], v[124:127], v[64:79]
	s_setprio 1
	s_add_i32 s4, s43, -2
	s_and_b32 s4, s4, 3
	s_mulk_i32 s4, 0x6000
	v_add_u32_e32 v246, s4, v158
	v_add_u32_e32 v250, v246, v151
	v_add_u32_e32 v251, v246, v149
	v_add_u32_e32 v252, v246, v148
	v_add_u32_e32 v253, v246, v147
	ds_read_b128 v[190:193], v250 offset:128
	ds_read_b128 v[194:197], v251 offset:128
	ds_read_b128 v[174:177], v250
	ds_read_b128 v[178:181], v251
	ds_read_b128 v[182:185], v252
	ds_read_b128 v[186:189], v253
	ds_read_b64_tr_b16 v[198:199], v254 offset:0x2000
	ds_read_b64_tr_b16 v[200:201], v254 offset:0x2800
	ds_read_b64_tr_b16 v[202:203], v254 offset:0x3000
	ds_read_b64_tr_b16 v[204:205], v254 offset:0x3800
	ds_read_b64_tr_b16 v[206:207], v254 offset:0x2200
	ds_read_b64_tr_b16 v[208:209], v254 offset:0x2a00
	ds_read_b64_tr_b16 v[210:211], v254 offset:0x3200
	ds_read_b64_tr_b16 v[212:213], v254 offset:0x3a00
	ds_read_b64_tr_b16 v[214:215], v254 offset:0x2400
	ds_read_b64_tr_b16 v[216:217], v254 offset:0x2c00
	ds_read_b64_tr_b16 v[218:219], v254 offset:0x3400
	ds_read_b64_tr_b16 v[220:221], v254 offset:0x3c00
	ds_read_b64_tr_b16 v[222:223], v254 offset:0x2600
	ds_read_b64_tr_b16 v[224:225], v254 offset:0x2e00
	ds_read_b64_tr_b16 v[226:227], v254 offset:0x3600
	ds_read_b64_tr_b16 v[228:229], v254 offset:0x3e00
	s_setprio 2
	v_exp_f32_e32 v64, v64
	v_exp_f32_e32 v65, v65
	v_exp_f32_e32 v66, v66
	v_exp_f32_e32 v67, v67
	v_exp_f32_e32 v68, v68
	v_exp_f32_e32 v69, v69
	v_add_f32_e32 v230, v65, v64
	v_exp_f32_e32 v70, v70
	v_add_f32_e32 v230, v66, v230
	v_exp_f32_e32 v71, v71
	v_add_f32_e32 v230, v67, v230
	v_exp_f32_e32 v72, v72
	v_add_f32_e32 v230, v68, v230
	v_exp_f32_e32 v73, v73
	v_add_f32_e32 v230, v69, v230
	v_exp_f32_e32 v74, v74
	v_add_f32_e32 v230, v70, v230
	v_exp_f32_e32 v75, v75
	v_add_f32_e32 v230, v71, v230
	v_exp_f32_e32 v76, v76
	v_add_f32_e32 v230, v72, v230
	v_exp_f32_e32 v77, v77
	v_add_f32_e32 v230, v73, v230
	v_exp_f32_e32 v78, v78
	v_add_f32_e32 v230, v74, v230
	v_exp_f32_e32 v79, v79
	v_add_f32_e32 v230, v75, v230
	v_add_f32_e32 v230, v76, v230
	v_add_f32_e32 v230, v77, v230
	v_add_f32_e32 v230, v78, v230
	v_add_f32_e32 v230, v79, v230
	v_add_f32_e32 v173, v173, v230
	v_cvt_pk_bf16_f32 v64, v64, v65
	v_cvt_pk_bf16_f32 v65, v66, v67
	v_cvt_pk_bf16_f32 v66, v68, v69
	v_cvt_pk_bf16_f32 v67, v70, v71
	v_cvt_pk_bf16_f32 v68, v72, v73
	v_cvt_pk_bf16_f32 v69, v74, v75
	v_cvt_pk_bf16_f32 v70, v76, v77
	v_cvt_pk_bf16_f32 v71, v78, v79
	s_waitcnt lgkmcnt(0)
	ds_read_b128 v[230:233], v252 offset:128
	ds_read_b128 v[234:237], v253 offset:128
	ds_read_b128 v[238:241], v250 offset:256
	ds_read_b128 v[242:245], v251 offset:256
	ds_read_b128 v[246:249], v252 offset:256
	ds_read_b128 v[250:253], v253 offset:256
	s_setprio 3
	s_waitcnt vmcnt(5)
	s_barrier
	v_mfma_f32_32x32x16_bf16 v[48:63], v[64:67], v[198:201], v[48:63]
	v_mfma_f32_32x32x16_bf16 v[32:47], v[64:67], v[206:209], v[32:47]
	v_mfma_f32_32x32x16_bf16 v[16:31], v[64:67], v[214:217], v[16:31]
	v_mfma_f32_32x32x16_bf16 v[0:15], v[64:67], v[222:225], v[0:15]
	v_mfma_f32_32x32x16_bf16 v[48:63], v[68:71], v[202:205], v[48:63]
	v_mfma_f32_32x32x16_bf16 v[32:47], v[68:71], v[210:213], v[32:47]
	v_mfma_f32_32x32x16_bf16 v[16:31], v[68:71], v[218:221], v[16:31]
	v_mfma_f32_32x32x16_bf16 v[0:15], v[68:71], v[226:229], v[0:15]
	s_waitcnt lgkmcnt(0)
	v_mfma_f32_32x32x16_bf16 v[64:79], v[174:177], v[80:83], 0
	v_mfma_f32_32x32x16_bf16 v[64:79], v[178:181], v[84:87], v[64:79]
	v_mfma_f32_32x32x16_bf16 v[64:79], v[182:185], v[88:91], v[64:79]
	v_mfma_f32_32x32x16_bf16 v[64:79], v[186:189], v[92:95], v[64:79]
	v_mfma_f32_32x32x16_bf16 v[64:79], v[190:193], v[96:99], v[64:79]
	v_mfma_f32_32x32x16_bf16 v[64:79], v[194:197], v[100:103], v[64:79]
	v_mfma_f32_32x32x16_bf16 v[64:79], v[230:233], v[104:107], v[64:79]
	v_mfma_f32_32x32x16_bf16 v[64:79], v[234:237], v[108:111], v[64:79]
	v_mfma_f32_32x32x16_bf16 v[64:79], v[238:241], v[112:115], v[64:79]
	v_mfma_f32_32x32x16_bf16 v[64:79], v[242:245], v[116:119], v[64:79]
	v_mfma_f32_32x32x16_bf16 v[64:79], v[246:249], v[120:123], v[64:79]
	v_mfma_f32_32x32x16_bf16 v[64:79], v[250:253], v[124:127], v[64:79]
	s_add_i32 s43, s43, 1
	v_add_u32_e32 v136, s36, v136
	v_add_u32_e32 v138, s36, v138
	v_add_u32_e32 v140, s36, v140
	v_add_u32_e32 v142, s38, v142
	v_add_u32_e32 v144, s38, v144
	s_cmp_eq_u32 s43, 64
	s_mov_b32 s4, s0
	s_cbranch_scc0 .Lhw_mla_b_n1982
	s_branch .Lhw_mla_exit
